# P3->P4 grid barrier also replaced by per-panel arrival counters (CNT word 2), on top of v087
# speedup vs baseline: 1.0066x; 1.0010x over previous
; #define PG8_BAR __builtin_amdgcn_s_barrier()
; template <class Epi, class Sched, bool ALIGN_EPI = false, bool SP2 = false>
; __device__ __forceinline__ void gemm_phase(PG8_LAS unsigned char* lds, const Gemm g, const Sched& S, const Epi& E, const int wave_) {
;     ...
;         if constexpr (!Epi::AFTER_DRAIN) { E(acc, cur, wr, wc, fr, fq); S.done(cur); }
;         if (!has_next) break;
; #pragma unroll
;         for (int a = 0; a < 2; ++a)
; #pragma unroll
;             for (int b = 0; b < 2; ++b)
; #pragma unroll
;                 for (int m = 0; m < 4; ++m)
; #pragma unroll
;                     for (int n = 0; n < 2; ++n) acc[a][b][m][n] = (f32x4){0.f, 0.f, 0.f, 0.f};
;         cur = nxt; cA = nA; cB = nB; ++ui;
;         if constexpr (ALIGN_EPI) { if (wr == 1) PG8_BAR; }
.LBB0_421:
	s_or_b64 exec, exec, s[24:25]
	v_readlane_b32 s100, v248, 35
	s_cmpk_lg_i32 s100, 0x100
	s_cbranch_scc1 .Lp3_noarr
	s_waitcnt vmcnt(0)
	s_lshl_b32 s98, s26, 8
	s_add_i32 s98, s98, 8
	v_mov_b32_e32 v236, s98
	v_mov_b32_e32 v237, 1
	s_add_u32 s98, s82, 0x310000
	s_addc_u32 s99, s83, 0
	s_mov_b64 s[100:101], exec
	s_mov_b64 exec, 1
	global_atomic_add v236, v237, s[98:99]
	s_mov_b64 exec, s[100:101]
.Lp3_noarr:
	s_andn2_b64 vcc, exec, s[4:5]
	s_mov_b64 s[4:5], -1
	s_cbranch_vccnz .LBB0_394
	s_andn2_b64 vcc, exec, s[10:11]
	s_cbranch_vccnz .LBB0_393
	s_barrier
	s_branch .LBB0_393

; __device__ __forceinline__ int tid_of(int wave) { return wave * 64 + lane_id(); }
; #define SEAM(k) do { if (IN(k) && IN((k) + 1)) xcd_barrier(bar); } while (0)
; __device__ __forceinline__ void xcd_barrier(const XcdBarrier& b) {
;     asm volatile("s_waitcnt vmcnt(0)" ::: "memory");
;     __syncthreads();
;     if (tid_of(b.w) == 0) {
;         unsigned* bar = b.bar;
;         __builtin_amdgcn_s_waitcnt(0);
;         unsigned nloc = b.st[0], nx = b.st[1];
;         if (nloc == 0u) { xcd_barrier_complete(bar, b.x, nloc, nx); b.st[0] = nloc; b.st[1] = nx; }
; __global__ void __launch_bounds__(NWAVES * 64, 2) fwd_kernel(Args a) {
;     ...
;     SEAM(3);
.LBB0_425:
	v_readlane_b32 s12, v248, 0
	v_readlane_b32 s13, v248, 1
	s_cmp_gt_i32 s13, 4
	s_cselect_b64 s[0:1], -1, 0
	s_and_b64 s[4:5], s[6:7], s[0:1]
	s_andn2_b64 vcc, exec, s[4:5]
	v_readlane_b32 s14, v248, 2
	v_readlane_b32 s15, v248, 3
	v_readlane_b32 s98, v248, 35
	s_cmpk_eq_i32 s98, 0x100
	s_cbranch_scc1 .LBB0_479
	s_cbranch_vccnz .LBB0_479
	s_waitcnt vmcnt(0)
	s_waitcnt vmcnt(0) lgkmcnt(0)
	s_barrier
	s_and_saveexec_b64 s[4:5], s[76:77]
	s_cbranch_execz .LBB0_478
	s_add_i32 s6, 0, 0x24fe0
	v_mov_b32_e32 v0, s6
	s_waitcnt vmcnt(0) expcnt(0) lgkmcnt(0)
	ds_read_b32 v2, v0
	s_add_i32 s6, 0, 0x24fe4
	v_mov_b32_e32 v0, s6
	ds_read_b32 v0, v0
	s_waitcnt lgkmcnt(1)
	v_cmp_ne_u32_e32 vcc, 0, v2
	s_cbranch_vccnz .LBB0_442
	s_add_u32 s6, s68, 0x1000
	s_addc_u32 s7, s69, 0
	s_add_u32 s10, s68, 0x1100
	s_addc_u32 s11, s69, 0
	s_add_u32 s12, s68, 0x1200
	s_addc_u32 s13, s69, 0
	s_mul_i32 s22, s89, s90
	s_add_u32 s14, s68, 0x1300
	s_mul_i32 s22, s22, s88
	s_addc_u32 s15, s69, 0
	s_mov_b32 s23, 1
	v_mov_b32_e32 v16, 0
	s_branch .LBB0_430

; #define PG8_STAGE(bufoff, gbase, voff) do { _Pragma("unroll") for (int _i = 0; _i < 2; ++_i) \
;         __builtin_amdgcn_global_load_lds((const unsigned*)((const char*)(gbase) + (voff)[_i]), (PG8_LAS unsigned*)(lds + (bufoff) + ldsw + _i * 8192), 16, 0, 0); } while (0)
; #define PG8_BAR __builtin_amdgcn_s_barrier()
; #define tid tid_of(wave)
; template <class Epi, class Sched, bool ALIGN_EPI = false, bool SP2 = false>
; __device__ __forceinline__ void gemm_phase(PG8_LAS unsigned char* lds, const Gemm g, const Sched& S, const Epi& E, const int wave_) {
;     ...
;     for (int i = 0; i < 2; ++i) { int R, C; stage_rc(tid * 16 + i * 8192, R, C); const int Rb = Epi::PERM ? ((R & ~31) + perm32(R & 31)) : R;
;         voffA[i] = (unsigned)(R * K + C) * 2u; voffB[i] = (unsigned)(Rb * K + C) * 2u; }
;     const size_t kstep = (size_t)(BK * 2);
;     const size_t hstep = (size_t)HALF * K * 2;
;     const size_t tstep = 2 * hstep;
;     const unsigned ldsw = (unsigned)wid * 1024u;
;     const int aoff = lds_byte(wr * 64 + fr, fq * 8), boff = lds_byte(wc * 32 + fr, fq * 8);
;     ...
;     Unit cur, nxt; int ui = 0;
;     if (!S.next(0, cur)) return;
;     f32x4 acc[2][2][4][2];
; #pragma unroll
;     for (int a = 0; a < 2; ++a)
; #pragma unroll
;         for (int b = 0; b < 2; ++b)
; #pragma unroll
;             for (int m = 0; m < 4; ++m)
; #pragma unroll
;                 for (int n = 0; n < 2; ++n) acc[a][b][m][n] = (f32x4){0.f, 0.f, 0.f, 0.f};
;     bf16x8 At[4][2], B0[2][2], B1[2][2];
;     const char* cA = (const char*)g.A + (size_t)cur.pm * tstep; const char* cB = (const char*)g.Bt + (size_t)cur.pn * tstep;
;     S.a_ready(cur);
;     if constexpr (SP2) {
;         PG8_STAGE(PG8_SB(0, 0), cB, voffB); PG8_STAGE(PG8_SB(0, 1), cB + hstep, voffB); PG8_STAGE(PG8_SA(0, 0), cA, voffA); PG8_STAGE(PG8_SA(0, 1), cA + hstep, voffA);
;         if (wr == 1) PG8_BAR;
.LBB0_482:
	s_andn2_b64 vcc, exec, s[0:1]
	s_cbranch_vccnz .LBB0_534
	v_readlane_b32 s100, v248, 35
	s_cmpk_lg_i32 s100, 0x100
	s_cbranch_scc1 .Lp4_nowait
	v_readlane_b32 s100, v248, 0
	s_cmp_gt_i32 s100, 3
	s_cbranch_scc1 .Lp4_nowait
	s_lshl_b32 s98, s4, 8
	s_add_i32 s98, s98, 8
	v_mov_b32_e32 v236, s98
	s_add_u32 s98, s82, 0x310000
	s_addc_u32 s99, s83, 0
	s_mov_b32 s100, 0
.Lp4_poll:
	global_load_dword v237, v236, s[98:99] sc1
	s_waitcnt vmcnt(0)
	v_readfirstlane_b32 s101, v237
	s_cmpk_ge_u32 s101, 0x40
	s_cbranch_scc1 .Lp4_nowait
	s_add_i32 s100, s100, 1
	s_cmp_lt_u32 s100, 0x10000
	s_cbranch_scc0 .Lp4_nowait
	s_sleep 2
	s_branch .Lp4_poll
.Lp4_nowait:
	s_lshr_b32 s98, s6, 2
	s_add_i32 s99, s6, s98
	s_and_b32 s99, s99, 3
	s_lshl_b32 s99, s99, 3
	s_and_b32 s98, s98, 3
	s_add_i32 s99, s99, s98
	s_lshr_b32 s98, s6, 4
	s_lshl_b32 s98, s98, 2
	s_add_i32 s6, s99, s98
	v_readlane_b32 s1, v248, 22
	s_lshl_b32 s44, s1, 10
	v_lshl_add_u32 v0, v195, 4, s44
	s_waitcnt lgkmcnt(0)
	v_ashrrev_i32_e32 v1, 31, v0
	v_lshrrev_b32_e32 v1, 22, v1
	v_add_u32_e32 v1, v0, v1
	v_ashrrev_i32_e32 v8, 10, v1
	v_mul_i32_i24_e32 v1, 0x400, v8
	v_sub_u32_e32 v1, v0, v1
	v_lshrrev_b32_e32 v2, 4, v1
	v_bitop3_b32 v1, v2, v1, 32 bitop3:0x6c
	v_ashrrev_i32_e32 v3, 31, v1
	v_lshrrev_b32_e32 v3, 26, v3
	v_add_u32_e32 v3, v1, v3
	v_lshlrev_b32_e32 v2, 3, v8
	v_ashrrev_i32_e32 v9, 6, v3
	v_and_b32_e32 v3, 0xc0, v3
	v_and_b32_e32 v2, -16, v2
	v_sub_u32_e32 v1, v1, v3
	v_mov_b32_e32 v3, 1
	v_add_u32_e32 v2, v9, v2
	v_ashrrev_i16_sdwa v1, v3, sext(v1) dst_sel:DWORD dst_unused:UNUSED_PAD src0_sel:DWORD src1_sel:BYTE_0
	v_lshlrev_b32_e32 v4, 5, v8
	v_bfe_i32 v10, v1, 0, 16
	v_lshlrev_b32_e32 v1, 1, v2
	v_lshrrev_b32_e32 v5, 2, v2
	v_and_b32_e32 v6, 3, v9
	s_mov_b32 s1, 0xfffe0
	v_and_b32_e32 v4, 32, v4
	v_and_b32_e32 v1, 24, v1
	v_and_b32_e32 v5, 4, v5
	v_and_or_b32 v6, v2, s1, v6
	v_or3_b32 v1, v6, v5, v1
	v_add_lshl_u32 v4, v4, v10, 1
	v_add_u32_e32 v0, 0x2000, v0
	v_lshl_add_u32 v130, v1, 12, v4
	v_ashrrev_i32_e32 v1, 31, v0
	v_lshrrev_b32_e32 v1, 22, v1
	v_add_u32_e32 v1, v0, v1
	v_ashrrev_i32_e32 v11, 10, v1
	v_mul_i32_i24_e32 v1, 0x400, v11
	v_sub_u32_e32 v0, v0, v1
	v_lshrrev_b32_e32 v1, 4, v0
	v_bitop3_b32 v0, v1, v0, 32 bitop3:0x6c
	v_lshl_add_u32 v128, v2, 12, v4
	v_ashrrev_i32_e32 v2, 31, v0
	v_lshrrev_b32_e32 v2, 26, v2
	v_add_u32_e32 v2, v0, v2
	v_ashrrev_i32_e32 v12, 6, v2
	v_and_b32_e32 v2, 0xffc0, v2
	s_lshr_b32 s0, s67, 8
	v_sub_u32_e32 v0, v0, v2
	v_lshrrev_b16_e32 v2, 7, v0
	s_cmp_eq_u32 s0, 1
	v_lshlrev_b32_e32 v1, 3, v11
	v_and_b32_e32 v2, 1, v2
	s_cselect_b64 s[12:13], -1, 0
	s_ashr_i32 s5, s4, 31
	s_ashr_i32 s7, s6, 31
	v_and_b32_e32 v1, -16, v1
	v_add_u16_e32 v0, v0, v2
	s_lshl_b64 s[14:15], s[4:5], 20
	s_lshl_b64 s[16:17], s[6:7], 20
	v_readlane_b32 s18, v248, 31
	v_add_u32_e32 v1, v12, v1
	v_ashrrev_i16_sdwa v0, v3, sext(v0) dst_sel:DWORD dst_unused:UNUSED_PAD src0_sel:DWORD src1_sel:BYTE_0
	v_readlane_b32 s19, v248, 32
	s_add_u32 s40, s18, s16
	v_lshlrev_b32_e32 v4, 5, v11
	v_bfe_i32 v13, v0, 0, 16
	v_lshlrev_b32_e32 v0, 1, v1
	v_lshrrev_b32_e32 v2, 2, v1
	v_and_b32_e32 v3, 3, v12
	s_addc_u32 s41, s19, s17
	s_add_i32 s45, s44, 0
	v_and_b32_e32 v4, 32, v4
	v_and_b32_e32 v0, 24, v0
	v_and_b32_e32 v2, 4, v2
	v_and_or_b32 v3, v1, s1, v3
	s_add_i32 m0, s45, 0x10000
	s_add_i32 s1, s45, 0x12000
	v_or3_b32 v0, v3, v2, v0
	v_add_lshl_u32 v2, v4, v13, 1
	s_add_u32 s16, s40, 0x80000
	v_lshl_add_u32 v134, v0, 12, v2
	s_addc_u32 s17, s41, 0
	s_add_i32 s5, s45, 0x14000
	s_add_i32 s7, s45, 0x16000
	global_load_lds_dwordx4 v130, s[40:41]
	s_mov_b32 m0, s1
	s_add_u32 s36, s38, s14
	global_load_lds_dwordx4 v134, s[40:41]
	s_mov_b32 m0, s5
	s_addc_u32 s37, s39, s15
	s_add_i32 s46, s45, 0x2000
	global_load_lds_dwordx4 v130, s[16:17]
	s_mov_b32 m0, s7
	s_add_u32 s14, s36, 0x80000
	global_load_lds_dwordx4 v134, s[16:17]
	s_mov_b32 m0, s45
	v_lshl_add_u32 v132, v1, 12, v2
	s_addc_u32 s15, s37, 0
	s_add_i32 s47, s45, 0x4000
	global_load_lds_dwordx4 v128, s[36:37]
	s_mov_b32 m0, s46
	s_add_i32 s48, s45, 0x6000
	global_load_lds_dwordx4 v132, s[36:37]
	s_mov_b32 m0, s47
	v_mov_b32_e32 v137, 0
	global_load_lds_dwordx4 v128, s[14:15]
	s_mov_b32 m0, s48
	v_mov_b32_e32 v131, v137
	global_load_lds_dwordx4 v132, s[14:15]
	v_mov_b32_e32 v135, v137
	v_mov_b32_e32 v129, v137
	v_mov_b32_e32 v133, v137
	s_mov_b32 s49, 0
	s_mov_b64 s[14:15], 0x80000
	s_cmp_lg_u32 s0, 1
	v_lshl_add_u64 v[6:7], s[40:41], 0, v[130:131]
	v_lshl_add_u64 v[4:5], s[40:41], 0, v[134:135]
	v_lshl_add_u64 v[2:3], s[36:37], 0, v[128:129]
	v_lshl_add_u64 v[0:1], s[36:37], 0, v[132:133]
	s_cbranch_scc1 .LBB0_485
	s_barrier
